# gate/up weight transposes in the pc phase: waves 4-7 run them before their pc items, waves 0-3 after, so each SIMD pairs a memory-bound wave with a compute wave
# speedup vs baseline: 1.0011x; 1.0011x over previous
; #define LAS __attribute__((address_space(3)))
; __device__ __forceinline__ void pc_phase(LAS unsigned char* lds, const bf16* Pp_, const bf16* LO, const float* mu, const float* w0, const float* a0, const float* k_k, const float* k_a, const float* r_k, ...
;     LAS bf16* XKK = (LAS bf16*)(lds + wave * PC_WAVE_LDS); LAS bf16* XR = XKK + 1152; LAS bf16* XK = XR + 1152; LAS bf16* XB = XK + 1152;
;     LAS float* AKB = (LAS float*)(XB + 1152); LAS float* AKK = AKB + 320; LAS float* ARK = AKK + 272; LAS float* ARB = ARK + 272; LAS float* TT = ARB + 272; LAS float* M1 = TT + 272; LAS float* PCL = M1 + 272;
;     ...
;     const int m = lane & 15, g = lane >> 4; const f32x4 zero = {0.f, 0.f, 0.f, 0.f};
;     for (int item = bid * NWAVES + wave; item < 16384; item += G * NWAVES) {
;         const size_t ib = (size_t)item * 16;
;         const int bh = item >> 8, c = item & 255, b = bh >> 4, h = bh & 15, ch = h * 64 + lane; const int m0 = b * SEQ + c * 16;
;         const float mu_r = mu[ch], mu_k = mu[1024 + ch], mu_v = mu[2048 + ch], w0c = w0[ch], a0c = a0[ch], kkc = k_k[ch], kac = k_a[ch], rkc = r_k[ch];
;         unsigned short sr_[17], sk_[17], sv_[17], slw[16], sla[16];
;         { const bf16* pp = Pp_ + (size_t)(c > 0 ? m0 - 1 : m0) * EV_IN_P + 3072 + ch; sr_[0] = pp[0]; sk_[0] = pp[1024]; sv_[0] = pp[2048]; }
; #pragma unroll
;         for (int t = 0; t < 16; ++t) { const bf16* pr = Pp_ + (size_t)(m0 + t) * EV_IN_P + 3072 + ch; sr_[t + 1] = pr[0]; sk_[t + 1] = pr[1024]; sv_[t + 1] = pr[2048];
;             const bf16* lo = LO + (size_t)(m0 + t) * LORA_N + ch; slw[t] = lo[0]; sla[t] = lo[1024]; }
;         const float z1 = (c > 0) ? 1.0f : 0.0f;
;         float P = 1.0f, r1 = bf2f(sr_[0]) * z1, k1 = bf2f(sk_[0]) * z1, v1 = bf2f(sv_[0]) * z1;
; #pragma unroll
;         for (int t = 0; t < 16; ++t) {
;             const float r0 = bf2f(sr_[t + 1]), k0 = bf2f(sk_[t + 1]), v0 = bf2f(sv_[t + 1]);
;             const float r = r0 + (r1 - r0) * mu_r, k = k0 + (k1 - k0) * mu_k, v = v0 + (v1 - v0) * mu_v; r1 = r0; k1 = k0; v1 = v0;
;             const float z = -(w0c + bf2f(slw[t])); const float sp = fmaxf(z, 0.f) + flog(1.0f + fexp(-fabsf(z))); const float w = -sp - 0.5f;
;             const float dec = fexp(-fexp(w)); const float a = fsigmoid(a0c + bf2f(sla[t]));
;             float kk = k * kkc; const float n2 = wsum_dpp(kk * kk); kk = kk / fmaxf(sqrtf(n2), 1e-12f);
.LBB0_275:
	s_andn2_b64 vcc, exec, s[0:1]
	s_cbranch_vccnz .LBB0_320
	s_cmp_lt_i32 s77, 11
	s_mov_b64 s[0:1], -1
	s_cbranch_scc1 .LBB0_315
	s_cmp_eq_u32 s77, 11
	s_cbranch_scc0 .LBB0_314
	s_cmp_ge_u32 s52, 4
	s_cbranch_scc0 .Ltrp_back
	s_mov_b32 s19, 1
	s_branch .Ltrp_begin
.Ltrp_back:
	s_add_i32 s0, s92, 0
	s_waitcnt vmcnt(0)
	v_mov_b32_e32 v2, s0
	s_waitcnt lgkmcnt(0)
	ds_read_b64 v[0:1], v2 offset:40
	s_cmpk_gt_i32 s10, 0x3fff
	s_waitcnt lgkmcnt(0)
	v_readfirstlane_b32 s0, v1
	v_readfirstlane_b32 s1, v0
	ds_read_b64 v[0:1], v2 offset:48
	s_waitcnt lgkmcnt(0)
	v_readfirstlane_b32 s2, v1
	v_readfirstlane_b32 s4, v0
	ds_read_b64 v[0:1], v2 offset:64
	s_waitcnt lgkmcnt(0)
	v_readfirstlane_b32 s5, v1
	v_readfirstlane_b32 s6, v0
	ds_read_b64 v[0:1], v2 offset:88
	s_waitcnt lgkmcnt(0)
	v_readfirstlane_b32 s7, v1
	v_readfirstlane_b32 s8, v0
	ds_read_b64 v[0:1], v2 offset:96
	s_waitcnt lgkmcnt(0)
	v_readfirstlane_b32 s9, v1
	v_readfirstlane_b32 s11, v0
	ds_read_b64 v[0:1], v2 offset:104
	s_waitcnt lgkmcnt(0)
	v_readfirstlane_b32 s14, v1
	v_readfirstlane_b32 s15, v0
	s_cbranch_scc1 .LBB0_314
	v_writelane_b32 v255, s80, 17
	s_mul_i32 s17, s96, 0x3480
	s_add_u32 s30, s1, s17
	v_writelane_b32 v255, s81, 18
	v_writelane_b32 v255, s43, 19
	s_addc_u32 s31, s0, 0
	v_writelane_b32 v255, s30, 13
	s_lshl_b32 s0, s96, 12
	v_and_b32_e32 v0, 15, v186
	v_writelane_b32 v255, s31, 14
	s_add_u32 s30, s4, s0
	s_addc_u32 s31, s2, 0
	v_writelane_b32 v255, s30, 15
	s_add_u32 s4, s6, s0
	s_addc_u32 s5, s5, 0
	v_writelane_b32 v255, s31, 16
	v_writelane_b32 v255, s4, 20
	v_lshrrev_b32_e32 v1, 4, v185
	v_lshlrev_b32_e32 v3, 2, v1
	v_writelane_b32 v255, s5, 21
	s_add_u32 s4, s8, s0
	s_addc_u32 s5, s7, 0
	v_writelane_b32 v255, s4, 22
	v_or_b32_e32 v7, 48, v185
	v_cmp_eq_u32_e32 vcc, 0, v0
	v_writelane_b32 v255, s5, 23
	s_add_u32 s4, s11, s0
	s_addc_u32 s5, s9, 0
	v_writelane_b32 v255, s4, 24
	s_add_u32 s0, s15, s0
	s_addc_u32 s1, s14, 0
	v_writelane_b32 v255, s5, 25
	v_writelane_b32 v255, s0, 26
	s_add_u32 s49, s88, 0x31e00000
	s_addc_u32 s35, s89, 0
	v_writelane_b32 v255, s1, 27
	s_mul_i32 s0, s52, 0x3f40
	s_add_i32 s28, s0, 0
	v_lshl_add_u32 v23, v0, 2, s28
	s_movk_i32 s0, 0x8c
	v_mad_u32_u24 v4, v0, s0, v23
	s_movk_i32 s0, 0x120
	v_mad_u32_u24 v8, v1, s0, v7
	v_cmp_lt_u32_e64 s[0:1], v0, v3
	v_or_b32_e32 v10, 1, v3
	v_cndmask_b32_e64 v24, 0, 1.0, vcc
	v_writelane_b32 v255, s0, 28
	v_cmp_eq_u32_e32 vcc, 14, v0
	v_mul_u32_u24_e32 v12, 17, v10
	v_writelane_b32 v255, s1, 29
	v_cmp_gt_u32_e64 s[0:1], v0, v10
	v_cndmask_b32_e64 v26, 0, 1.0, vcc
	v_lshl_add_u32 v31, v12, 2, v23
	v_writelane_b32 v255, s0, 30
	v_or_b32_e32 v12, 2, v3
	v_cmp_eq_u32_e32 vcc, 1, v0
	v_writelane_b32 v255, s1, 31
	v_cmp_lt_u32_e64 s[0:1], v0, v12
	v_cndmask_b32_e64 v34, 0, 1.0, vcc
	v_cmp_eq_u32_e32 vcc, 2, v0
	v_writelane_b32 v255, s0, 32
	v_mad_u32_u24 v5, v0, 17, v3
	v_cndmask_b32_e64 v35, 0, 1.0, vcc
	v_cmp_eq_u32_e32 vcc, 3, v0
	v_writelane_b32 v255, s1, 33
	v_cmp_gt_u32_e64 s[0:1], v0, v12
	v_cndmask_b32_e64 v36, 0, 1.0, vcc
	v_cmp_eq_u32_e32 vcc, 4, v0
	v_cmp_gt_u32_e64 s[42:43], v0, v3
	v_writelane_b32 v255, s0, 34
	v_or_b32_e32 v3, 3, v3
	v_cndmask_b32_e64 v37, 0, 1.0, vcc
	v_cmp_eq_u32_e32 vcc, 5, v0
	v_writelane_b32 v255, s1, 35
	v_cmp_lt_u32_e64 s[0:1], v0, v3
	v_cndmask_b32_e64 v38, 0, 1.0, vcc
	v_cmp_eq_u32_e32 vcc, 6, v0
	v_mul_u32_u24_e32 v6, 0x120, v1
	v_and_b32_e32 v9, 48, v185
	v_writelane_b32 v255, s0, 36
	v_cndmask_b32_e64 v39, 0, 1.0, vcc
	v_cmp_eq_u32_e32 vcc, 7, v0
	v_add_u32_e32 v28, v4, v9
	v_mul_u32_u24_e32 v9, 0x140, v1
	v_mul_u32_u24_e32 v29, 0x44, v1
	v_writelane_b32 v255, s1, 37
	v_cndmask_b32_e64 v40, 0, 1.0, vcc
	v_cmp_eq_u32_e32 vcc, 8, v0
	v_lshl_add_u32 v48, v1, 3, v4
	v_or_b32_e32 v1, v6, v0
	s_movk_i32 s0, 0x48
	v_cndmask_b32_e64 v41, 0, 1.0, vcc
	v_cmp_eq_u32_e32 vcc, 9, v0
	v_lshl_add_u32 v50, v1, 1, s28
	v_mad_u32_u24 v1, v10, s0, v0
	v_cndmask_b32_e64 v42, 0, 1.0, vcc
	v_cmp_eq_u32_e32 vcc, 10, v0
	v_lshl_add_u32 v51, v1, 1, s28
	v_mad_u32_u24 v1, v10, s0, s0
	v_cmp_gt_u32_e64 s[46:47], v0, v3
	v_cndmask_b32_e64 v43, 0, 1.0, vcc
	v_cmp_eq_u32_e32 vcc, 11, v0
	v_or_b32_e32 v3, v1, v0
	v_lshl_add_u32 v52, v3, 1, s28
	v_cndmask_b32_e64 v44, 0, 1.0, vcc
	v_cmp_eq_u32_e32 vcc, 12, v0
	v_mov_b32_e32 v3, 0x90
	v_mad_u32_u24 v3, v10, s0, v3
	v_cndmask_b32_e64 v45, 0, 1.0, vcc
	v_cmp_eq_u32_e32 vcc, 13, v0
	v_add_u32_e32 v4, v3, v0
	s_ashr_i32 s11, s10, 31
	v_cndmask_b32_e64 v46, 0, 1.0, vcc
	v_cmp_eq_u32_e32 vcc, 15, v0
	v_add_u32_e32 v0, v1, v0
	v_lshl_add_u32 v54, v0, 1, s28
	v_mad_u32_u24 v0, v10, s0, v7
	v_lshl_add_u32 v56, v0, 1, s28
	v_add_u32_e32 v0, v1, v7
	s_mul_i32 s1, s10, 0x2900
	v_lshlrev_b32_e32 v2, 2, v185
	v_lshl_add_u32 v57, v0, 1, s28
	v_add_u32_e32 v0, v3, v7
	s_mul_hi_i32 s0, s10, 0x2900
	s_add_u32 s1, s1, 0x27602800
	v_add_u32_e32 v22, s28, v2
	v_lshlrev_b32_e32 v96, 4, v185
	v_lshl_add_u32 v58, v0, 1, s28
	s_addc_u32 s0, s0, 0
	v_or_b32_e32 v0, s1, v2
	v_mov_b32_e32 v2, 0x2900
	v_mov_b32_e32 v1, s0
	v_mad_i64_i32 v[2:3], s[0:1], s10, v2, v[96:97]
	v_lshl_add_u32 v25, v8, 1, s28
	v_lshlrev_b32_e32 v8, 1, v185
	v_mul_u32_u24_e32 v11, 0x50, v10
	s_lshl_b64 s[0:1], s[10:11], 11
	v_cmp_eq_u32_e64 s[38:39], 0, v185
	v_sub_u32_e32 v27, v22, v8
	v_lshl_add_u32 v30, v29, 2, v23
	v_add_u32_e32 v32, 0x44, v31
	v_add_u32_e32 v33, 0x88, v31
	v_cndmask_b32_e64 v47, 0, 1.0, vcc
	v_lshl_add_u32 v49, v5, 2, s28
	v_lshl_add_u32 v53, v4, 1, s28
	v_lshl_add_u32 v55, v7, 2, s28
	v_or_b32_e32 v4, s0, v8
	v_mov_b32_e32 v5, s1
	v_add_u32_e32 v59, v23, v9
	v_add_u32_e32 v60, v23, v11
	s_mov_b32 s11, s10
	s_mov_b32 s19, 0xbfb8aa3b
	s_mov_b32 s33, 0xf800000
	s_branch .LBB0_281

; #define INF(i) uniform_ptr((const float*)tab[i])
; __global__ void __launch_bounds__(NTHREADS, 2) trunk_fwd(Args a) {
;     ...
;                 for (int q = 0; q < 2; ++q) { const int LL = L + q; bf16* fgu = (bf16*)(ws + WS_FGU + (size_t)(LL & 1) * SZ_FFN); bf16* fd = (bf16*)(ws + WS_FD + (size_t)(LL & 1) * SZ_FFN);
;                     tr_matrix(INF(27) + (size_t)LL * D * DFF, D, DFF, fgu, D, 0, 1, 0, scr, cw, ncw, lane, nullptr, INF(26) + (size_t)LL * D);
;                     tr_matrix(INF(28) + (size_t)LL * D * DFF, D, DFF, fgu, D, 0, 1, 128, scr, cw, ncw, lane, nullptr, INF(26) + (size_t)LL * D);
.LBB0_314:
	s_cmp_eq_u32 s77, 11
	s_cbranch_scc0 .Ltrp_skip
	s_cmp_ge_u32 s52, 4
	s_cbranch_scc1 .Ltrp_skip
	s_mov_b32 s19, 0
.Ltrp_begin:
	v_lshrrev_b32_e32 v1, 3, v185
	v_and_b32_e32 v2, 7, v185
	v_mul_u32_u24_e32 v3, 0x5800, v1
	v_lshl_add_u32 v20, v2, 4, v3
	v_add_u32_e32 v21, 0x2c000, v20
	v_add_u32_e32 v22, 0x58000, v20
	v_add_u32_e32 v23, 0x84000, v20
	v_add_u32_e32 v24, 0xb0000, v20
	v_add_u32_e32 v25, 0xdc000, v20
	v_add_u32_e32 v26, 0x108000, v20
	v_add_u32_e32 v27, 0x134000, v20
	v_lshlrev_b32_e32 v28, 2, v1
	s_mul_i32 s0, s52, 0x3f40
	v_mul_u32_u24_e32 v3, 0x84, v1
	v_lshl_add_u32 v3, v2, 4, v3
	v_add_u32_e32 v29, s0, v3
	v_mul_u32_u24_e32 v3, 0x420, v2
	v_lshl_add_u32 v3, v1, 2, v3
	v_add_u32_e32 v30, s0, v3
	v_lshlrev_b32_e32 v3, 12, v1
	v_lshl_add_u32 v31, v2, 4, v3
	v_add_u32_e32 v32, 0x8000, v31
	v_add_u32_e32 v33, 0x10000, v31
	v_add_u32_e32 v34, 0x18000, v31
	s_mov_b32 s56, 0

; #define INF(i) uniform_ptr((const float*)tab[i])
; __global__ void __launch_bounds__(NTHREADS, 2) trunk_fwd(Args a) {
;     ...
;                 for (int q = 0; q < 2; ++q) { const int LL = L + q; bf16* fgu = (bf16*)(ws + WS_FGU + (size_t)(LL & 1) * SZ_FFN); bf16* fd = (bf16*)(ws + WS_FD + (size_t)(LL & 1) * SZ_FFN);
;                     tr_matrix(INF(27) + (size_t)LL * D * DFF, D, DFF, fgu, D, 0, 1, 0, scr, cw, ncw, lane, nullptr, INF(26) + (size_t)LL * D);
;                     tr_matrix(INF(28) + (size_t)LL * D * DFF, D, DFF, fgu, D, 0, 1, 128, scr, cw, ncw, lane, nullptr, INF(26) + (size_t)LL * D);
;                     tr_matrix(INF(29) + (size_t)LL * DFF * D, DFF, D, fd, DFF, 0, 0, 0, scr, cw, ncw, lane); }
.Ltrp_mat_next:
	s_add_i32 s5, s5, 1
	s_cmp_lt_u32 s5, 2
	s_cbranch_scc1 .Ltrp_mat
	s_add_i32 s56, s56, 1
	s_cmp_lt_u32 s56, 2
	s_cbranch_scc1 .Ltrp_q
	s_cmp_lg_u32 s19, 0
	s_cbranch_scc1 .Ltrp_back
